# code placement: the three GEMM K-loop heads and the attention inner-loop head padded to 64-byte alignment with s_nop (executed once per tile / unit)
# baseline (speedup 1.0000x reference)
; #define LAS __attribute__((address_space(3)))
; #define MFMA32(a, b, c) __builtin_amdgcn_mfma_f32_32x32x16_bf16((a), (b), (c), 0, 0, 0)
; #define AT_LOAD(S, kt, vt) do { const int kt_ = (kt) < nt ? (kt) : nt - 1, vt_ = (vt) < nt ? (vt) : nt - 1; const bf16_t* Kt_ = Kh + (size_t)kt_ * 64 * 96; \
;         rk##S##0 = *(const u32x4*)(Kt_ + kc0 * 8); rk##S##1 = *(const u32x4*)(Kt_ + kc1c * 8); rv##S = *(const u32x4*)(Vh + (size_t)vd * TK + vt_ * 64 + vch * 8); } while (0)
; #define AT_STOREK(S, bb) do { LAS unsigned char* Kn_ = lds + (bb) * AT_KB; *(LAS u32x4*)(Kn_ + kl0) = rk##S##0; if (tid < 256) *(LAS u32x4*)(Kn_ + kl1) = rk##S##1; } while (0)
; #define AT_STOREV(S, bb) do { *(LAS u32x4*)(lds + 2 * AT_KB + (bb) * AT_VB + vl) = rv##S; } while (0)
; DI void attn_phase(const bf16_t* Qb, const bf16_t* Kb, const bf16_t* VT, bf16_t* MIX, LAS unsigned char* lds, int G, int bid, int tid, int wave, int lane) {
;     ...
;         float lsum = 0.f;
;         f32x16 o0, o1, sA0, sA1, sB0, sB1;
; #pragma unroll
;         for (int r = 0; r < 16; ++r) { o0[r] = 0.f; o1[r] = 0.f; }
;         auto qk = [&](f32x16& s0, f32x16& s1, const int kbuf) __attribute__((always_inline)) {
;             const LAS unsigned char* Kl = lds + kbuf * AT_KB;
;             f32x16 z;
; #pragma unroll
;             for (int r = 0; r < 16; ++r) z[r] = 0.f;
; #pragma unroll
;             for (int d0 = 0; d0 < 6; ++d0) {
;                 const bf16x8 a0 = *(const LAS bf16x8*)(Kl + r32 * 208 + d0 * 32 + hi * 16);
;                 const bf16x8 a1 = *(const LAS bf16x8*)(Kl + (32 + r32) * 208 + d0 * 32 + hi * 16);
;                 if (d0 == 0) { s0 = MFMA32(a0, qf[0], z); s1 = MFMA32(a1, qf[0], z); }
;                 else { s0 = MFMA32(a0, qf[d0], s0); s1 = MFMA32(a1, qf[d0], s1); }
;             }
;         };
;     ...
;         AT_LOAD(A, 0, 0); AT_LOAD(B, 1, 1);
;         AT_STOREK(A, 0); AT_STOREV(A, 0); AT_STOREK(B, 1);
;         AT_LOAD(B, 2, 1);
;         __syncthreads();
;         qk(sA0, sA1, 0);
;         __syncthreads();
.LBB0_453:
	s_or_b64 exec, exec, s[38:39]
	s_add_i32 s31, s30, -1
	s_add_u32 s26, s8, 0x6000
	s_addc_u32 s27, s9, 0
	s_waitcnt vmcnt(2)
	v_lshl_add_u64 v[0:1], v[160:161], 1, s[26:27]
	global_load_dwordx4 v[104:107], v215, s[26:27]
	global_load_dwordx4 v[112:115], v[0:1], off
	global_load_dwordx4 v[96:99], v[198:199], off offset:128
	s_waitcnt lgkmcnt(0)
	s_barrier
	ds_read_b128 v[0:3], v219
	s_waitcnt vmcnt(3)
	ds_read_b128 v[4:7], v219 offset:32
	s_waitcnt lgkmcnt(1)
	v_mfma_f32_32x32x16_bf16 v[48:63], v[0:3], v[128:131], 0
	ds_read_b128 v[0:3], v219 offset:6656
	ds_read_b128 v[8:11], v219 offset:6688
	s_mul_hi_i32 s27, s44, 0x88000
	s_mul_i32 s26, s44, 0x88000
	v_mov_b32_e32 v167, 0
	v_lshl_add_u64 v[200:201], v[164:165], 0, s[26:27]
	s_mov_b32 s38, 4
	v_mov_b32_e32 v16, 0
	s_waitcnt lgkmcnt(2)
	v_mfma_f32_32x32x16_bf16 v[48:63], v[4:7], v[124:127], v[48:63]
	v_mov_b32_e32 v17, v167
	v_mov_b32_e32 v22, v167
	v_mov_b32_e32 v23, v167
	v_mov_b32_e32 v28, v167
	v_mov_b32_e32 v29, v167
	v_mov_b32_e32 v30, v167
	v_mov_b32_e32 v31, v167
	s_waitcnt lgkmcnt(1)
	v_mfma_f32_32x32x16_bf16 v[32:47], v[0:3], v[128:131], 0
	ds_read_b128 v[0:3], v219 offset:64
	ds_read_b128 v[4:7], v219 offset:96
	s_waitcnt lgkmcnt(1)
	v_mfma_f32_32x32x16_bf16 v[48:63], v[0:3], v[120:123], v[48:63]
	ds_read_b128 v[0:3], v219 offset:6720
	v_mfma_f32_32x32x16_bf16 v[32:47], v[8:11], v[124:127], v[32:47]
	ds_read_b128 v[8:11], v219 offset:6752
	ds_read_b128 v[18:21], v219 offset:6784
	ds_read_b128 v[64:67], v219 offset:6816
	ds_read_b128 v[12:15], v219 offset:128
	ds_read_b128 v[24:27], v219 offset:160
	s_waitcnt lgkmcnt(0)
	s_barrier
	v_mfma_f32_32x32x16_bf16 v[32:47], v[0:3], v[120:123], v[32:47]
	v_mov_b32_e32 v0, 0
	v_mov_b32_e32 v1, v167
	v_mov_b32_e32 v2, v167
	v_mov_b32_e32 v3, v167
	v_mfma_f32_32x32x16_bf16 v[48:63], v[4:7], v[116:119], v[48:63]
	v_mov_b32_e32 v4, v167
	v_mov_b32_e32 v5, v167
	v_mov_b32_e32 v6, v167
	v_mov_b32_e32 v7, v167
	v_mfma_f32_32x32x16_bf16 v[32:47], v[8:11], v[116:119], v[32:47]
	v_mov_b32_e32 v8, v167
	v_mov_b32_e32 v9, v167
	v_mov_b32_e32 v10, v167
	v_mov_b32_e32 v11, v167
	v_mfma_f32_32x32x16_bf16 v[48:63], v[12:15], v[108:111], v[48:63]
	v_mov_b32_e32 v12, v167
	v_mov_b32_e32 v13, v167
	v_mov_b32_e32 v14, v167
	v_mov_b32_e32 v15, v167
	v_mfma_f32_32x32x16_bf16 v[32:47], v[18:21], v[108:111], v[32:47]
	v_mov_b32_e32 v18, v167
	v_mov_b32_e32 v19, v167
	v_mov_b32_e32 v20, v167
	v_mov_b32_e32 v21, v167
	v_mfma_f32_32x32x16_bf16 v[48:63], v[24:27], v[100:103], v[48:63]
	v_mov_b32_e32 v24, v167
	v_mov_b32_e32 v25, v167
	v_mov_b32_e32 v26, v167
	v_mov_b32_e32 v27, v167
	v_mfma_f32_32x32x16_bf16 v[32:47], v[64:67], v[100:103], v[32:47]
	s_nop 0
	s_nop 0
	s_nop 0
	s_nop 0
	s_nop 0
	s_nop 0
	s_nop 0
	s_nop 0
	s_nop 0
	s_nop 0

; template <class Epi>
; DI void gemm_phase(LAS unsigned char* lds, const int tid, const Gemm g, const StaticOrder& S, const Epi& E) {
;     ...
;     for (;;) {
;         const bool has_next = S.next(ui + 1, nxt);
;         const char* nA = has_next ? (const char*)g.A + (size_t)nxt.pm * tstA + (size_t)nxt.ks * ksb : cA; const char* nB = has_next ? (const char*)g.Bt + (size_t)nxt.pn * tstB + (size_t)nxt.ks * ksb : cB;
;         for (int t = 0; t < nt; t += 2) {
;             const bool last = (t == nt - 2);
;             const char* a1 = cA + (size_t)(t + 1) * kstep;
;             const char* a2 = last ? nA : cA + (size_t)(t + 2) * kstep; const char* b2 = last ? nB : cB + (size_t)(t + 2) * kstep;
;             const char* a3 = a2 + kstep; const char* b3 = b2 + kstep;
;     ...
; #pragma unroll
;         for (int a = 0; a < 2; ++a)
; #pragma unroll
;             for (int b = 0; b < 2; ++b)
; #pragma unroll
;                 for (int m = 0; m < 4; ++m)
; #pragma unroll
;                     for (int n = 0; n < 2; ++n) acc[a][b][m][n] = (f32x4){0.f, 0.f, 0.f, 0.f};
;         cur = nxt; cA = nA; cB = nB; ++ui;
.LBB0_664:
	v_mov_b32_e32 v127, 0
	s_andn2_b64 vcc, exec, s[60:61]
	v_mov_b32_e32 v126, v127
	v_mov_b32_e32 v125, v127
	v_mov_b32_e32 v124, v127
	v_mov_b32_e32 v131, v127
	v_mov_b32_e32 v130, v127
	v_mov_b32_e32 v129, v127
	v_mov_b32_e32 v128, v127
	v_mov_b32_e32 v119, v127
	v_mov_b32_e32 v118, v127
	v_mov_b32_e32 v117, v127
	v_mov_b32_e32 v116, v127
	v_mov_b32_e32 v123, v127
	v_mov_b32_e32 v122, v127
	v_mov_b32_e32 v121, v127
	v_mov_b32_e32 v120, v127
	v_mov_b32_e32 v111, v127
	v_mov_b32_e32 v110, v127
	v_mov_b32_e32 v109, v127
	v_mov_b32_e32 v108, v127
	v_mov_b32_e32 v115, v127
	v_mov_b32_e32 v114, v127
	v_mov_b32_e32 v113, v127
	v_mov_b32_e32 v112, v127
	v_mov_b32_e32 v103, v127
	v_mov_b32_e32 v102, v127
	v_mov_b32_e32 v101, v127
	v_mov_b32_e32 v100, v127
	v_mov_b32_e32 v107, v127
	v_mov_b32_e32 v106, v127
	v_mov_b32_e32 v105, v127
	v_mov_b32_e32 v104, v127
	v_mov_b32_e32 v59, v127
	v_mov_b32_e32 v58, v127
	v_mov_b32_e32 v57, v127
	v_mov_b32_e32 v56, v127
	v_mov_b32_e32 v63, v127
	v_mov_b32_e32 v62, v127
	v_mov_b32_e32 v61, v127
	v_mov_b32_e32 v60, v127
	v_mov_b32_e32 v51, v127
	v_mov_b32_e32 v50, v127
	v_mov_b32_e32 v49, v127
	v_mov_b32_e32 v48, v127
	v_mov_b32_e32 v55, v127
	v_mov_b32_e32 v54, v127
	v_mov_b32_e32 v53, v127
	v_mov_b32_e32 v52, v127
	v_mov_b32_e32 v43, v127
	v_mov_b32_e32 v42, v127
	v_mov_b32_e32 v41, v127
	v_mov_b32_e32 v40, v127
	v_mov_b32_e32 v47, v127
	v_mov_b32_e32 v46, v127
	v_mov_b32_e32 v45, v127
	v_mov_b32_e32 v44, v127
	v_mov_b32_e32 v35, v127
	v_mov_b32_e32 v34, v127
	v_mov_b32_e32 v33, v127
	v_mov_b32_e32 v32, v127
	v_mov_b32_e32 v39, v127
	v_mov_b32_e32 v38, v127
	v_mov_b32_e32 v37, v127
	v_mov_b32_e32 v36, v127
	v_mov_b32_e32 v95, v127
	v_mov_b32_e32 v94, v127
	v_mov_b32_e32 v93, v127
	v_mov_b32_e32 v92, v127
	v_mov_b32_e32 v99, v127
	v_mov_b32_e32 v98, v127
	v_mov_b32_e32 v97, v127
	v_mov_b32_e32 v96, v127
	v_mov_b32_e32 v83, v127
	v_mov_b32_e32 v82, v127
	v_mov_b32_e32 v81, v127
	v_mov_b32_e32 v80, v127
	v_mov_b32_e32 v91, v127
	v_mov_b32_e32 v90, v127
	v_mov_b32_e32 v89, v127
	v_mov_b32_e32 v88, v127
	v_mov_b32_e32 v75, v127
	v_mov_b32_e32 v74, v127
	v_mov_b32_e32 v73, v127
	v_mov_b32_e32 v72, v127
	v_mov_b32_e32 v79, v127
	v_mov_b32_e32 v78, v127
	v_mov_b32_e32 v77, v127
	v_mov_b32_e32 v76, v127
	v_mov_b32_e32 v67, v127
	v_mov_b32_e32 v66, v127
	v_mov_b32_e32 v65, v127
	v_mov_b32_e32 v64, v127
	v_mov_b32_e32 v71, v127
	v_mov_b32_e32 v70, v127
	v_mov_b32_e32 v69, v127
	v_mov_b32_e32 v68, v127
	v_mov_b32_e32 v27, v127
	v_mov_b32_e32 v26, v127
	v_mov_b32_e32 v25, v127
	v_mov_b32_e32 v24, v127
	v_mov_b32_e32 v31, v127
	v_mov_b32_e32 v30, v127
	v_mov_b32_e32 v29, v127
	v_mov_b32_e32 v28, v127
	v_mov_b32_e32 v19, v127
	v_mov_b32_e32 v18, v127
	v_mov_b32_e32 v17, v127
	v_mov_b32_e32 v16, v127
	v_mov_b32_e32 v23, v127
	v_mov_b32_e32 v22, v127
	v_mov_b32_e32 v21, v127
	v_mov_b32_e32 v20, v127
	v_mov_b32_e32 v11, v127
	v_mov_b32_e32 v10, v127
	v_mov_b32_e32 v9, v127
	v_mov_b32_e32 v8, v127
	v_mov_b32_e32 v15, v127
	v_mov_b32_e32 v14, v127
	v_mov_b32_e32 v13, v127
	v_mov_b32_e32 v12, v127
	v_mov_b32_e32 v3, v127
	v_mov_b32_e32 v2, v127
	v_mov_b32_e32 v1, v127
	v_mov_b32_e32 v0, v127
	v_mov_b32_e32 v7, v127
	v_mov_b32_e32 v6, v127
	v_mov_b32_e32 v5, v127
	v_mov_b32_e32 v4, v127
	s_cbranch_vccnz .LBB0_667
	s_add_u32 s26, s26, 0x80
	s_addc_u32 s27, s27, 0
	s_add_u32 s68, s66, 0x100
	s_addc_u32 s69, s67, 0
	s_mov_b32 s66, 0
	s_nop 0
	s_nop 0
	s_nop 0
	s_nop 0
	s_nop 0
	s_nop 0
	s_nop 0
	s_nop 0
	s_nop 0
	s_nop 0

; template <class Epi>
; DI void gemm_phase(LAS unsigned char* lds, const int tid, const Gemm g, const StaticOrder& S, const Epi& E) {
;     ...
;     for (;;) {
;         const bool has_next = S.next(ui + 1, nxt);
;         const char* nA = has_next ? (const char*)g.A + (size_t)nxt.pm * tstA + (size_t)nxt.ks * ksb : cA; const char* nB = has_next ? (const char*)g.Bt + (size_t)nxt.pn * tstB + (size_t)nxt.ks * ksb : cB;
;         for (int t = 0; t < nt; t += 2) {
;             const bool last = (t == nt - 2);
;             const char* a1 = cA + (size_t)(t + 1) * kstep;
;             const char* a2 = last ? nA : cA + (size_t)(t + 2) * kstep; const char* b2 = last ? nB : cB + (size_t)(t + 2) * kstep;
;             const char* a3 = a2 + kstep; const char* b3 = b2 + kstep;
;     ...
; #pragma unroll
;         for (int a = 0; a < 2; ++a)
; #pragma unroll
;             for (int b = 0; b < 2; ++b)
; #pragma unroll
;                 for (int m = 0; m < 4; ++m)
; #pragma unroll
;                     for (int n = 0; n < 2; ++n) acc[a][b][m][n] = (f32x4){0.f, 0.f, 0.f, 0.f};
;         cur = nxt; cA = nA; cB = nB; ++ui;
.LBB0_696:
	v_mov_b32_e32 v127, 0
	s_andn2_b64 vcc, exec, s[62:63]
	v_mov_b32_e32 v126, v127
	v_mov_b32_e32 v125, v127
	v_mov_b32_e32 v124, v127
	v_mov_b32_e32 v123, v127
	v_mov_b32_e32 v122, v127
	v_mov_b32_e32 v121, v127
	v_mov_b32_e32 v120, v127
	v_mov_b32_e32 v119, v127
	v_mov_b32_e32 v118, v127
	v_mov_b32_e32 v117, v127
	v_mov_b32_e32 v116, v127
	v_mov_b32_e32 v115, v127
	v_mov_b32_e32 v114, v127
	v_mov_b32_e32 v113, v127
	v_mov_b32_e32 v112, v127
	v_mov_b32_e32 v111, v127
	v_mov_b32_e32 v110, v127
	v_mov_b32_e32 v109, v127
	v_mov_b32_e32 v108, v127
	v_mov_b32_e32 v107, v127
	v_mov_b32_e32 v106, v127
	v_mov_b32_e32 v105, v127
	v_mov_b32_e32 v104, v127
	v_mov_b32_e32 v103, v127
	v_mov_b32_e32 v102, v127
	v_mov_b32_e32 v101, v127
	v_mov_b32_e32 v100, v127
	v_mov_b32_e32 v99, v127
	v_mov_b32_e32 v98, v127
	v_mov_b32_e32 v97, v127
	v_mov_b32_e32 v96, v127
	v_mov_b32_e32 v63, v127
	v_mov_b32_e32 v62, v127
	v_mov_b32_e32 v61, v127
	v_mov_b32_e32 v60, v127
	v_mov_b32_e32 v59, v127
	v_mov_b32_e32 v58, v127
	v_mov_b32_e32 v57, v127
	v_mov_b32_e32 v56, v127
	v_mov_b32_e32 v55, v127
	v_mov_b32_e32 v54, v127
	v_mov_b32_e32 v53, v127
	v_mov_b32_e32 v52, v127
	v_mov_b32_e32 v51, v127
	v_mov_b32_e32 v50, v127
	v_mov_b32_e32 v49, v127
	v_mov_b32_e32 v48, v127
	v_mov_b32_e32 v47, v127
	v_mov_b32_e32 v46, v127
	v_mov_b32_e32 v45, v127
	v_mov_b32_e32 v44, v127
	v_mov_b32_e32 v43, v127
	v_mov_b32_e32 v42, v127
	v_mov_b32_e32 v41, v127
	v_mov_b32_e32 v40, v127
	v_mov_b32_e32 v39, v127
	v_mov_b32_e32 v38, v127
	v_mov_b32_e32 v37, v127
	v_mov_b32_e32 v36, v127
	v_mov_b32_e32 v35, v127
	v_mov_b32_e32 v34, v127
	v_mov_b32_e32 v33, v127
	v_mov_b32_e32 v32, v127
	v_mov_b32_e32 v95, v127
	v_mov_b32_e32 v94, v127
	v_mov_b32_e32 v93, v127
	v_mov_b32_e32 v92, v127
	v_mov_b32_e32 v91, v127
	v_mov_b32_e32 v90, v127
	v_mov_b32_e32 v89, v127
	v_mov_b32_e32 v88, v127
	v_mov_b32_e32 v87, v127
	v_mov_b32_e32 v86, v127
	v_mov_b32_e32 v85, v127
	v_mov_b32_e32 v84, v127
	v_mov_b32_e32 v83, v127
	v_mov_b32_e32 v82, v127
	v_mov_b32_e32 v81, v127
	v_mov_b32_e32 v80, v127
	v_mov_b32_e32 v79, v127
	v_mov_b32_e32 v78, v127
	v_mov_b32_e32 v77, v127
	v_mov_b32_e32 v76, v127
	v_mov_b32_e32 v75, v127
	v_mov_b32_e32 v74, v127
	v_mov_b32_e32 v73, v127
	v_mov_b32_e32 v72, v127
	v_mov_b32_e32 v71, v127
	v_mov_b32_e32 v70, v127
	v_mov_b32_e32 v69, v127
	v_mov_b32_e32 v68, v127
	v_mov_b32_e32 v67, v127
	v_mov_b32_e32 v66, v127
	v_mov_b32_e32 v65, v127
	v_mov_b32_e32 v64, v127
	v_mov_b32_e32 v31, v127
	v_mov_b32_e32 v30, v127
	v_mov_b32_e32 v29, v127
	v_mov_b32_e32 v28, v127
	v_mov_b32_e32 v27, v127
	v_mov_b32_e32 v26, v127
	v_mov_b32_e32 v25, v127
	v_mov_b32_e32 v24, v127
	v_mov_b32_e32 v23, v127
	v_mov_b32_e32 v22, v127
	v_mov_b32_e32 v21, v127
	v_mov_b32_e32 v20, v127
	v_mov_b32_e32 v19, v127
	v_mov_b32_e32 v18, v127
	v_mov_b32_e32 v17, v127
	v_mov_b32_e32 v16, v127
	v_mov_b32_e32 v15, v127
	v_mov_b32_e32 v14, v127
	v_mov_b32_e32 v13, v127
	v_mov_b32_e32 v12, v127
	v_mov_b32_e32 v11, v127
	v_mov_b32_e32 v10, v127
	v_mov_b32_e32 v9, v127
	v_mov_b32_e32 v8, v127
	v_mov_b32_e32 v7, v127
	v_mov_b32_e32 v6, v127
	v_mov_b32_e32 v5, v127
	v_mov_b32_e32 v4, v127
	v_mov_b32_e32 v3, v127
	v_mov_b32_e32 v2, v127
	v_mov_b32_e32 v1, v127
	v_mov_b32_e32 v0, v127
	s_cbranch_vccnz .LBB0_699
	s_add_u32 s26, s26, 0x80
	s_addc_u32 s27, s27, 0
	s_add_u32 vcc_lo, s68, 0x100
	s_addc_u32 vcc_hi, s69, 0
	s_mov_b32 s68, 0
	s_nop 0
	s_nop 0
	s_nop 0
	s_nop 0
	s_nop 0
	s_nop 0
	s_nop 0
	s_nop 0
	s_nop 0
	s_nop 0
	s_nop 0
	s_nop 0
	s_nop 0

; template <class Epi>
; DI void gemm_phase(LAS unsigned char* lds, const int tid, const Gemm g, const StaticOrder& S, const Epi& E) {
;     ...
;     for (;;) {
;         const bool has_next = S.next(ui + 1, nxt);
;         const char* nA = has_next ? (const char*)g.A + (size_t)nxt.pm * tstA + (size_t)nxt.ks * ksb : cA; const char* nB = has_next ? (const char*)g.Bt + (size_t)nxt.pn * tstB + (size_t)nxt.ks * ksb : cB;
;         for (int t = 0; t < nt; t += 2) {
;             const bool last = (t == nt - 2);
;             const char* a1 = cA + (size_t)(t + 1) * kstep;
;             const char* a2 = last ? nA : cA + (size_t)(t + 2) * kstep; const char* b2 = last ? nB : cB + (size_t)(t + 2) * kstep;
;             const char* a3 = a2 + kstep; const char* b3 = b2 + kstep;
;     ...
; #pragma unroll
;         for (int a = 0; a < 2; ++a)
; #pragma unroll
;             for (int b = 0; b < 2; ++b)
; #pragma unroll
;                 for (int m = 0; m < 4; ++m)
; #pragma unroll
;                     for (int n = 0; n < 2; ++n) acc[a][b][m][n] = (f32x4){0.f, 0.f, 0.f, 0.f};
;         cur = nxt; cA = nA; cB = nB; ++ui;
.LBB0_759:
	v_mov_b32_e32 v123, 0
	s_andn2_b64 vcc, exec, s[38:39]
	v_mov_b32_e32 v122, v123
	v_mov_b32_e32 v121, v123
	v_mov_b32_e32 v120, v123
	v_mov_b32_e32 v127, v123
	v_mov_b32_e32 v126, v123
	v_mov_b32_e32 v125, v123
	v_mov_b32_e32 v124, v123
	v_mov_b32_e32 v111, v123
	v_mov_b32_e32 v110, v123
	v_mov_b32_e32 v109, v123
	v_mov_b32_e32 v108, v123
	v_mov_b32_e32 v107, v123
	v_mov_b32_e32 v106, v123
	v_mov_b32_e32 v105, v123
	v_mov_b32_e32 v104, v123
	v_mov_b32_e32 v95, v123
	v_mov_b32_e32 v94, v123
	v_mov_b32_e32 v93, v123
	v_mov_b32_e32 v92, v123
	v_mov_b32_e32 v91, v123
	v_mov_b32_e32 v90, v123
	v_mov_b32_e32 v89, v123
	v_mov_b32_e32 v88, v123
	v_mov_b32_e32 v79, v123
	v_mov_b32_e32 v78, v123
	v_mov_b32_e32 v77, v123
	v_mov_b32_e32 v76, v123
	v_mov_b32_e32 v75, v123
	v_mov_b32_e32 v74, v123
	v_mov_b32_e32 v73, v123
	v_mov_b32_e32 v72, v123
	v_mov_b32_e32 v119, v123
	v_mov_b32_e32 v118, v123
	v_mov_b32_e32 v117, v123
	v_mov_b32_e32 v116, v123
	v_mov_b32_e32 v115, v123
	v_mov_b32_e32 v114, v123
	v_mov_b32_e32 v113, v123
	v_mov_b32_e32 v112, v123
	v_mov_b32_e32 v103, v123
	v_mov_b32_e32 v102, v123
	v_mov_b32_e32 v101, v123
	v_mov_b32_e32 v100, v123
	v_mov_b32_e32 v99, v123
	v_mov_b32_e32 v98, v123
	v_mov_b32_e32 v97, v123
	v_mov_b32_e32 v96, v123
	v_mov_b32_e32 v87, v123
	v_mov_b32_e32 v86, v123
	v_mov_b32_e32 v85, v123
	v_mov_b32_e32 v84, v123
	v_mov_b32_e32 v83, v123
	v_mov_b32_e32 v82, v123
	v_mov_b32_e32 v81, v123
	v_mov_b32_e32 v80, v123
	v_mov_b32_e32 v71, v123
	v_mov_b32_e32 v70, v123
	v_mov_b32_e32 v69, v123
	v_mov_b32_e32 v68, v123
	v_mov_b32_e32 v67, v123
	v_mov_b32_e32 v66, v123
	v_mov_b32_e32 v65, v123
	v_mov_b32_e32 v64, v123
	v_mov_b32_e32 v63, v123
	v_mov_b32_e32 v62, v123
	v_mov_b32_e32 v61, v123
	v_mov_b32_e32 v60, v123
	v_mov_b32_e32 v59, v123
	v_mov_b32_e32 v58, v123
	v_mov_b32_e32 v57, v123
	v_mov_b32_e32 v56, v123
	v_mov_b32_e32 v47, v123
	v_mov_b32_e32 v46, v123
	v_mov_b32_e32 v45, v123
	v_mov_b32_e32 v44, v123
	v_mov_b32_e32 v43, v123
	v_mov_b32_e32 v42, v123
	v_mov_b32_e32 v41, v123
	v_mov_b32_e32 v40, v123
	v_mov_b32_e32 v31, v123
	v_mov_b32_e32 v30, v123
	v_mov_b32_e32 v29, v123
	v_mov_b32_e32 v28, v123
	v_mov_b32_e32 v27, v123
	v_mov_b32_e32 v26, v123
	v_mov_b32_e32 v25, v123
	v_mov_b32_e32 v24, v123
	v_mov_b32_e32 v15, v123
	v_mov_b32_e32 v14, v123
	v_mov_b32_e32 v13, v123
	v_mov_b32_e32 v12, v123
	v_mov_b32_e32 v11, v123
	v_mov_b32_e32 v10, v123
	v_mov_b32_e32 v9, v123
	v_mov_b32_e32 v8, v123
	v_mov_b32_e32 v55, v123
	v_mov_b32_e32 v54, v123
	v_mov_b32_e32 v53, v123
	v_mov_b32_e32 v52, v123
	v_mov_b32_e32 v51, v123
	v_mov_b32_e32 v50, v123
	v_mov_b32_e32 v49, v123
	v_mov_b32_e32 v48, v123
	v_mov_b32_e32 v39, v123
	v_mov_b32_e32 v38, v123
	v_mov_b32_e32 v37, v123
	v_mov_b32_e32 v36, v123
	v_mov_b32_e32 v35, v123
	v_mov_b32_e32 v34, v123
	v_mov_b32_e32 v33, v123
	v_mov_b32_e32 v32, v123
	v_mov_b32_e32 v23, v123
	v_mov_b32_e32 v22, v123
	v_mov_b32_e32 v21, v123
	v_mov_b32_e32 v20, v123
	v_mov_b32_e32 v19, v123
	v_mov_b32_e32 v18, v123
	v_mov_b32_e32 v17, v123
	v_mov_b32_e32 v16, v123
	v_mov_b32_e32 v7, v123
	v_mov_b32_e32 v6, v123
	v_mov_b32_e32 v5, v123
	v_mov_b32_e32 v4, v123
	v_mov_b32_e32 v3, v123
	v_mov_b32_e32 v2, v123
	v_mov_b32_e32 v1, v123
	v_mov_b32_e32 v0, v123
	s_cbranch_vccnz .LBB0_762
	s_add_u32 s6, s64, 0x80
	s_addc_u32 s7, s65, 0
	s_add_u32 s30, s26, 0x100
	s_addc_u32 s31, s27, 0
	s_mov_b32 s26, 0
	s_nop 0
	s_nop 0
	s_nop 0
	s_nop 0
	s_nop 0
	s_nop 0
	s_nop 0
	s_nop 0
	s_nop 0
